# v051 with attention stagger s_sleep 8 instead of 12
# speedup vs baseline: 1.0087x; 1.0046x over previous
; #define ATT_ISSUE2(p_, st_) do { LAS unsigned char* sp_ = lds + (st_) * STG2; const int ta_ = dual ? (p_) : 2 * (p_), tb_ = dual ? (p_) : 2 * (p_) + 1; ATT_ISSUE1(u, ta_, sp_); ATT_ISSUEM(ta_, sp_ + 2 * STAGEB); \
;         if (dual || tb_ < u.ntiles) { ATT_ISSUE1(ub, tb_, sp_ + STAGEB); ATT_ISSUEM(tb_, sp_ + 2 * STAGEB + MSKB); } } while (0)
;     ...
;             asm volatile("s_waitcnt vmcnt(0)" ::: "memory");
;             __builtin_amdgcn_s_barrier(); asm volatile("" ::: "memory");
;             if (p + 1 < npairs) ATT_ISSUE2(p + 1, (p + 1) & 1);
.LBB0_579:
	s_add_i32 s27, s2, 1
	s_waitcnt vmcnt(0)
	s_barrier
	v_readlane_b32 s98, v254, 11
	s_nop 3
	s_cmp_lt_u32 s98, 4
	s_cbranch_scc1 .Lstag_579
	s_sleep 8

; #define ATT_ISSUE2(p_, st_) do { LAS unsigned char* sp_ = lds + (st_) * STG2; const int ta_ = dual ? (p_) : 2 * (p_), tb_ = dual ? (p_) : 2 * (p_) + 1; ATT_ISSUE1(u, ta_, sp_); ATT_ISSUEM(ta_, sp_ + 2 * STAGEB); \
;         if (dual || tb_ < u.ntiles) { ATT_ISSUE1(ub, tb_, sp_ + STAGEB); ATT_ISSUEM(tb_, sp_ + 2 * STAGEB + MSKB); } } while (0)
;     ...
;             asm volatile("s_waitcnt vmcnt(0)" ::: "memory");
;             __builtin_amdgcn_s_barrier(); asm volatile("" ::: "memory");
;             if (p + 1 < npairs) ATT_ISSUE2(p + 1, (p + 1) & 1);
.LBB0_2104:
	s_waitcnt vmcnt(0)
	s_barrier
	v_readlane_b32 s98, v254, 11
	s_nop 3
	s_cmp_lt_u32 s98, 4
	s_cbranch_scc1 .Lstag_2104
	s_sleep 8

; #define ATT_ISSUE2(p_, st_) do { LAS unsigned char* sp_ = lds + (st_) * STG2; const int ta_ = dual ? (p_) : 2 * (p_), tb_ = dual ? (p_) : 2 * (p_) + 1; ATT_ISSUE1(u, ta_, sp_); ATT_ISSUEM(ta_, sp_ + 2 * STAGEB); \
;         if (dual || tb_ < u.ntiles) { ATT_ISSUE1(ub, tb_, sp_ + STAGEB); ATT_ISSUEM(tb_, sp_ + 2 * STAGEB + MSKB); } } while (0)
;     ...
;             asm volatile("s_waitcnt vmcnt(0)" ::: "memory");
;             __builtin_amdgcn_s_barrier(); asm volatile("" ::: "memory");
;             if (p + 1 < npairs) ATT_ISSUE2(p + 1, (p + 1) & 1);
.LBB0_3301:
	s_add_i32 s96, s97, 1
	s_waitcnt vmcnt(0)
	s_barrier
	v_readlane_b32 s98, v254, 11
	s_nop 3
	s_cmp_lt_u32 s98, 4
	s_cbranch_scc1 .Lstag_3301
	s_sleep 8
